# lean in-proj tiles skip the K-loop-end barrier: epilogue slabs placed in ring buffers 0 and 2 (idle after the last K-stage barrier)
# speedup vs baseline: 1.0086x; 1.0021x over previous
.LBB0_220:
	s_cmp_gt_i32 s7, 0
	s_waitcnt vmcnt(6)
	s_cselect_b32 s8, -1, 2
	s_mul_i32 s9, s7, 0x6000
	s_waitcnt lgkmcnt(0)
	s_add_i32 s8, s8, s7
	v_add_u32_e32 v139, s9, v224
	v_add_u32_e32 v0, s9, v223
	s_mulk_i32 s8, 0x6000
	v_add_u32_e32 v154, v139, v228
	s_barrier
	v_lshl_add_u64 v[170:171], v[144:145], 0, s[2:3]
	v_add_u32_e32 v141, s8, v221
	v_lshl_add_u64 v[174:175], v[142:143], 0, s[2:3]
	v_add_u32_e32 v182, s8, v222
	v_add_u32_e32 v166, v0, v228
	ds_read_b128 v[146:149], v166
	ds_read_b128 v[150:153], v154
	ds_read_b128 v[154:157], v154 offset:2048
	v_lshl_add_u64 v[172:173], v[170:171], 0, s[88:89]
	v_lshl_add_u64 v[176:177], v[174:175], 0, s[88:89]
	v_add_u32_e32 v183, 0x4000, v182
	v_lshl_add_u64 v[178:179], v[170:171], 0, s[90:91]
	v_add_u32_e32 v184, 0x400, v141
	v_lshl_add_u64 v[180:181], v[170:171], 0, s[78:79]
	v_add_u32_e32 v185, 0x800, v141
	ds_read_b128 v[158:161], v166 offset:2048
	ds_read_b128 v[162:165], v166 offset:4096
	ds_read_b128 v[166:169], v166 offset:6144
	s_waitcnt lgkmcnt(3)
	s_setprio 1
	v_mfma_f32_32x32x16_bf16 v[114:129], v[146:149], v[150:153], v[114:129]
	v_mfma_f32_32x32x16_bf16 v[98:113], v[146:149], v[154:157], v[98:113]
	v_readfirstlane_b32 s8, v141
	s_mov_b32 m0, s8
	s_nop 0
	global_load_lds_dwordx4 v[172:173], off
	s_waitcnt lgkmcnt(2)
	v_mfma_f32_32x32x16_bf16 v[82:97], v[158:161], v[150:153], v[82:97]
	v_mfma_f32_32x32x16_bf16 v[66:81], v[158:161], v[154:157], v[66:81]
	v_readfirstlane_b32 s8, v184
	s_mov_b32 m0, s8
	s_nop 0
	global_load_lds_dwordx4 v[178:179], off
	s_waitcnt lgkmcnt(1)
	v_mfma_f32_32x32x16_bf16 v[50:65], v[162:165], v[150:153], v[50:65]
	v_mfma_f32_32x32x16_bf16 v[34:49], v[162:165], v[154:157], v[34:49]
	v_readfirstlane_b32 s8, v185
	s_mov_b32 m0, s8
	s_nop 0
	global_load_lds_dwordx4 v[180:181], off
	s_waitcnt lgkmcnt(0)
	v_mfma_f32_32x32x16_bf16 v[18:33], v[166:169], v[150:153], v[18:33]
	v_mfma_f32_32x32x16_bf16 v[2:17], v[166:169], v[154:157], v[2:17]
	s_setprio 0
	v_add_u32_e32 v0, v0, v229
	v_add_u32_e32 v139, v139, v229
	ds_read_b128 v[146:149], v0
	ds_read_b128 v[150:153], v139
	ds_read_b128 v[154:157], v139 offset:2048
	ds_read_b128 v[158:161], v0 offset:2048
	ds_read_b128 v[162:165], v0 offset:4096
	ds_read_b128 v[166:169], v0 offset:6144
	s_waitcnt lgkmcnt(3)
	s_setprio 1
	v_mfma_f32_32x32x16_bf16 v[114:129], v[146:149], v[150:153], v[114:129]
	v_mfma_f32_32x32x16_bf16 v[98:113], v[146:149], v[154:157], v[98:113]
	v_add_u32_e32 v0, 0xc00, v141
	v_lshl_add_u64 v[146:147], v[170:171], 0, s[76:77]
	v_readfirstlane_b32 s8, v0
	s_mov_b32 m0, s8
	s_nop 0
	global_load_lds_dwordx4 v[146:147], off
	s_waitcnt lgkmcnt(2)
	v_mfma_f32_32x32x16_bf16 v[82:97], v[158:161], v[150:153], v[82:97]
	v_mfma_f32_32x32x16_bf16 v[66:81], v[158:161], v[154:157], v[66:81]
	v_readfirstlane_b32 s8, v183
	s_mov_b32 m0, s8
	s_nop 0
	global_load_lds_dwordx4 v[176:177], off
	s_waitcnt lgkmcnt(1)
	v_mfma_f32_32x32x16_bf16 v[50:65], v[162:165], v[150:153], v[50:65]
	v_mfma_f32_32x32x16_bf16 v[34:49], v[162:165], v[154:157], v[34:49]
	v_add_u32_e32 v0, 0x4400, v182
	v_lshl_add_u64 v[146:147], v[174:175], 0, s[90:91]
	v_readfirstlane_b32 s8, v0
	s_mov_b32 m0, s8
	s_nop 0
	global_load_lds_dwordx4 v[146:147], off
	s_waitcnt lgkmcnt(0)
	v_mfma_f32_32x32x16_bf16 v[18:33], v[166:169], v[150:153], v[18:33]
	v_mfma_f32_32x32x16_bf16 v[2:17], v[166:169], v[154:157], v[2:17]
	s_setprio 0
	s_add_i32 s8, s7, 1
	s_cmp_lt_i32 s7, 2
	s_cselect_b32 s7, s8, 0
	s_add_u32 s2, s2, 0x80
	s_addc_u32 s3, s3, 0
	s_cmpk_eq_i32 s2, 0xf00
	s_cbranch_scc0 .LBB0_220
	s_waitcnt vmcnt(6)
	s_mul_i32 s2, s7, 0x6000
	s_waitcnt lgkmcnt(0)
	v_add_u32_e32 v139, s2, v224
	v_add_u32_e32 v0, s2, v223
	v_add_u32_e32 v150, v139, v228
	s_barrier
	v_add_u32_e32 v141, v0, v228
	ds_read_b128 v[142:145], v141
	ds_read_b128 v[146:149], v150
	ds_read_b128 v[150:153], v150 offset:2048
	ds_read_b128 v[154:157], v141 offset:2048
	ds_read_b128 v[158:161], v141 offset:4096
	ds_read_b128 v[162:165], v141 offset:6144
	s_waitcnt lgkmcnt(3)
	s_setprio 1
	v_mfma_f32_32x32x16_bf16 v[114:129], v[142:145], v[146:149], v[114:129]
	v_mfma_f32_32x32x16_bf16 v[98:113], v[142:145], v[150:153], v[98:113]
	s_waitcnt lgkmcnt(2)
	v_mfma_f32_32x32x16_bf16 v[82:97], v[154:157], v[146:149], v[82:97]
	v_mfma_f32_32x32x16_bf16 v[66:81], v[154:157], v[150:153], v[66:81]
	s_waitcnt lgkmcnt(1)
	v_mfma_f32_32x32x16_bf16 v[50:65], v[158:161], v[146:149], v[50:65]
	v_mfma_f32_32x32x16_bf16 v[34:49], v[158:161], v[150:153], v[34:49]
	s_waitcnt lgkmcnt(0)
	v_mfma_f32_32x32x16_bf16 v[18:33], v[162:165], v[146:149], v[18:33]
	v_mfma_f32_32x32x16_bf16 v[2:17], v[162:165], v[150:153], v[2:17]
	s_setprio 0
	v_add_u32_e32 v0, v0, v229
	v_add_u32_e32 v139, v139, v229
	ds_read_b128 v[142:145], v0
	ds_read_b128 v[146:149], v139
	ds_read_b128 v[150:153], v139 offset:2048
	ds_read_b128 v[154:157], v0 offset:2048
	ds_read_b128 v[158:161], v0 offset:4096
	ds_read_b128 v[162:165], v0 offset:6144
	s_waitcnt lgkmcnt(3)
	s_setprio 1
	v_mfma_f32_32x32x16_bf16 v[114:129], v[142:145], v[146:149], v[114:129]
	v_mfma_f32_32x32x16_bf16 v[98:113], v[142:145], v[150:153], v[98:113]
	s_waitcnt lgkmcnt(2)
	v_mfma_f32_32x32x16_bf16 v[82:97], v[154:157], v[146:149], v[82:97]
	v_mfma_f32_32x32x16_bf16 v[66:81], v[154:157], v[150:153], v[66:81]
	s_waitcnt lgkmcnt(1)
	v_mfma_f32_32x32x16_bf16 v[50:65], v[158:161], v[146:149], v[50:65]
	v_mfma_f32_32x32x16_bf16 v[34:49], v[158:161], v[150:153], v[34:49]
	s_waitcnt lgkmcnt(0)
	v_mfma_f32_32x32x16_bf16 v[18:33], v[162:165], v[146:149], v[18:33]
	v_mfma_f32_32x32x16_bf16 v[2:17], v[162:165], v[150:153], v[2:17]
	s_setprio 0
	s_waitcnt vmcnt(0)
	s_waitcnt lgkmcnt(0)
	s_barrier
	ds_read_b128 v[142:145], v232
	ds_read_b128 v[146:149], v233
	ds_read_b128 v[150:153], v233 offset:2048
	ds_read_b128 v[154:157], v232 offset:2048
	ds_read_b128 v[158:161], v232 offset:4096
	ds_read_b128 v[162:165], v232 offset:6144
	s_waitcnt lgkmcnt(3)
	s_setprio 1
	v_mfma_f32_32x32x16_bf16 v[114:129], v[142:145], v[146:149], v[114:129]
	v_mfma_f32_32x32x16_bf16 v[98:113], v[142:145], v[150:153], v[98:113]
	s_waitcnt lgkmcnt(2)
	v_mfma_f32_32x32x16_bf16 v[82:97], v[154:157], v[146:149], v[82:97]
	v_mfma_f32_32x32x16_bf16 v[66:81], v[154:157], v[150:153], v[66:81]
	s_waitcnt lgkmcnt(1)
	v_mfma_f32_32x32x16_bf16 v[50:65], v[158:161], v[146:149], v[50:65]
	v_mfma_f32_32x32x16_bf16 v[34:49], v[158:161], v[150:153], v[34:49]
	s_waitcnt lgkmcnt(0)
	v_mfma_f32_32x32x16_bf16 v[18:33], v[162:165], v[146:149], v[18:33]
	v_mfma_f32_32x32x16_bf16 v[2:17], v[162:165], v[150:153], v[2:17]
	s_setprio 0
	ds_read_b128 v[142:145], v234
	ds_read_b128 v[146:149], v235
	ds_read_b128 v[150:153], v235 offset:2048
	ds_read_b128 v[154:157], v234 offset:2048
	ds_read_b128 v[158:161], v234 offset:4096
	ds_read_b128 v[162:165], v234 offset:6144
	s_waitcnt lgkmcnt(3)
	s_setprio 1
	v_mfma_f32_32x32x16_bf16 v[114:129], v[142:145], v[146:149], v[114:129]
	v_mfma_f32_32x32x16_bf16 v[98:113], v[142:145], v[150:153], v[98:113]
	s_waitcnt lgkmcnt(2)
	v_mfma_f32_32x32x16_bf16 v[82:97], v[154:157], v[146:149], v[82:97]
	v_mfma_f32_32x32x16_bf16 v[66:81], v[154:157], v[150:153], v[66:81]
	s_waitcnt lgkmcnt(1)
	v_mfma_f32_32x32x16_bf16 v[50:65], v[158:161], v[146:149], v[50:65]
	v_mfma_f32_32x32x16_bf16 v[34:49], v[158:161], v[150:153], v[34:49]
	s_waitcnt lgkmcnt(0)
	v_mfma_f32_32x32x16_bf16 v[18:33], v[162:165], v[146:149], v[18:33]
	v_mfma_f32_32x32x16_bf16 v[2:17], v[162:165], v[150:153], v[2:17]
	s_setprio 0
	s_cmp_gt_i32 s4, 3
	s_cselect_b64 s[30:31], -1, 0
	s_add_i32 s2, s4, -8
	s_cmp_gt_u32 s2, 5
	s_cselect_b64 s[98:99], -1, 0
	s_and_b32 s2, s4, 0x7ffffffc
	s_cmp_lg_u32 s2, 20
	v_add_u32_e32 v238, s5, v225
	s_cselect_b64 s[2:3], -1, 0
	s_and_b32 s5, s4, 0x7ffffffe
	s_cmp_eq_u32 s5, 6
	s_cselect_b64 s[82:83], -1, 0
	s_sub_i32 s5, s4, 17
	v_add_u32_e32 v239, 0x800, v230
	v_add_u32_e32 v240, 0x1000, v230
	v_add_u32_e32 v241, 0x1800, v230
	s_mov_b32 s8, 0x0701c030
	s_mov_b32 s34, 0x380e00c0
	s_lshr_b32 s8, s8, s4
	s_lshr_b32 s34, s34, s4
	s_and_b32 s8, s8, 1
	s_and_b32 s34, s34, 1
	s_or_b32 s7, s8, s34
	s_cmp_eq_u32 s7, 0
	s_cbranch_scc1 .Lmy_g0e_std
	v_and_b32_e32 v151, 63, v200
	v_lshrrev_b32_e32 v150, 5, v151
	v_and_b32_e32 v146, 31, v151
	v_lshrrev_b32_e32 v147, 6, v200
	v_lshrrev_b32_e32 v152, 1, v147
	v_and_b32_e32 v148, 1, v147
	v_mul_u32_u24_e32 v147, 0x2200, v147
	s_movk_i32 s6, 0x7c00
	v_mad_u32_u24 v147, v152, s6, v147
	v_lshlrev_b32_e32 v146, 2, v146
	s_movk_i32 s6, 0x440
	v_mad_u32_u24 v146, v150, s6, v146
	v_add_u32_e32 v146, v146, v147
	v_lshrrev_b32_e32 v150, 3, v151
	v_and_b32_e32 v149, 7, v151
	s_movk_i32 s6, 0x110
	v_mad_u32_u24 v147, v150, s6, v147
	v_lshl_add_u32 v147, v149, 5, v147
	v_lshl_add_u32 v152, v152, 7, s32
	v_add_u32_e32 v152, v152, v150
	s_lshl_b32 s6, s4, 7
	v_lshl_add_u32 v148, v148, 6, s6
	v_lshl_add_u32 v148, v149, 3, v148
	v_lshlrev_b32_e32 v148, 1, v148
	v_mul_u32_u24_e32 v152, 0x1e00, v152
	v_add_u32_e32 v148, v148, v152
	s_mov_b64 s[8:9], s[64:65]
	s_cmp_eq_u32 s34, 1
	s_cbranch_scc1 .Lmy_g0e_gate
	ds_write2_b32 v146, v114, v98 offset0:0 offset1:32
	ds_write2_b32 v146, v115, v99 offset0:68 offset1:100
	ds_write2_b32 v146, v116, v100 offset0:136 offset1:168
	ds_write2_b32 v146, v117, v101 offset0:204 offset1:236
	v_add_u32_e32 v146, 0x880, v146
	ds_write2_b32 v146, v118, v102 offset0:0 offset1:32
	ds_write2_b32 v146, v119, v103 offset0:68 offset1:100
	ds_write2_b32 v146, v120, v104 offset0:136 offset1:168
	ds_write2_b32 v146, v121, v105 offset0:204 offset1:236
	v_add_u32_e32 v146, 0x880, v146
	ds_write2_b32 v146, v122, v106 offset0:0 offset1:32
	ds_write2_b32 v146, v123, v107 offset0:68 offset1:100
	ds_write2_b32 v146, v124, v108 offset0:136 offset1:168
	ds_write2_b32 v146, v125, v109 offset0:204 offset1:236
	v_add_u32_e32 v146, 0x880, v146
	ds_write2_b32 v146, v126, v110 offset0:0 offset1:32
	ds_write2_b32 v146, v127, v111 offset0:68 offset1:100
	ds_write2_b32 v146, v128, v112 offset0:136 offset1:168
	ds_write2_b32 v146, v129, v113 offset0:204 offset1:236
	v_subrev_u32_e32 v146, 0x1980, v146
	s_waitcnt lgkmcnt(0)
	ds_read_b128 v[98:101], v147
	ds_read_b128 v[102:105], v147 offset:16
	ds_read_b128 v[106:109], v147 offset:2176
	ds_read_b128 v[110:113], v147 offset:2192
	ds_read_b128 v[114:117], v147 offset:4352
	ds_read_b128 v[118:121], v147 offset:4368
	ds_read_b128 v[122:125], v147 offset:6528
	ds_read_b128 v[126:129], v147 offset:6544
	s_waitcnt lgkmcnt(6)
	v_cvt_pk_bf16_f32 v154, v98, v99
	v_cvt_pk_bf16_f32 v155, v100, v101
	v_cvt_pk_bf16_f32 v156, v102, v103
	v_cvt_pk_bf16_f32 v157, v104, v105
	global_store_dwordx4 v148, v[154:157], s[8:9]
	s_add_u32 s8, s8, 0xf000
	s_addc_u32 s9, s9, 0
	s_waitcnt lgkmcnt(4)
	v_cvt_pk_bf16_f32 v158, v106, v107
	v_cvt_pk_bf16_f32 v159, v108, v109
	v_cvt_pk_bf16_f32 v160, v110, v111
	v_cvt_pk_bf16_f32 v161, v112, v113
	global_store_dwordx4 v148, v[158:161], s[8:9]
	s_add_u32 s8, s8, 0xf000
	s_addc_u32 s9, s9, 0
	s_waitcnt lgkmcnt(2)
	v_cvt_pk_bf16_f32 v162, v114, v115
	v_cvt_pk_bf16_f32 v163, v116, v117
	v_cvt_pk_bf16_f32 v164, v118, v119
	v_cvt_pk_bf16_f32 v165, v120, v121
	global_store_dwordx4 v148, v[162:165], s[8:9]
	s_add_u32 s8, s8, 0xf000
	s_addc_u32 s9, s9, 0
	s_waitcnt lgkmcnt(0)
	v_cvt_pk_bf16_f32 v166, v122, v123
	v_cvt_pk_bf16_f32 v167, v124, v125
	v_cvt_pk_bf16_f32 v168, v126, v127
	v_cvt_pk_bf16_f32 v169, v128, v129
	global_store_dwordx4 v148, v[166:169], s[8:9]
	s_add_u32 s8, s8, 0xf000
	s_addc_u32 s9, s9, 0
	ds_write2_b32 v146, v82, v66 offset0:0 offset1:32
	ds_write2_b32 v146, v83, v67 offset0:68 offset1:100
	ds_write2_b32 v146, v84, v68 offset0:136 offset1:168
	ds_write2_b32 v146, v85, v69 offset0:204 offset1:236
	v_add_u32_e32 v146, 0x880, v146
	ds_write2_b32 v146, v86, v70 offset0:0 offset1:32
	ds_write2_b32 v146, v87, v71 offset0:68 offset1:100
	ds_write2_b32 v146, v88, v72 offset0:136 offset1:168
	ds_write2_b32 v146, v89, v73 offset0:204 offset1:236
	v_add_u32_e32 v146, 0x880, v146
	ds_write2_b32 v146, v90, v74 offset0:0 offset1:32
	ds_write2_b32 v146, v91, v75 offset0:68 offset1:100
	ds_write2_b32 v146, v92, v76 offset0:136 offset1:168
	ds_write2_b32 v146, v93, v77 offset0:204 offset1:236
	v_add_u32_e32 v146, 0x880, v146
	ds_write2_b32 v146, v94, v78 offset0:0 offset1:32
	ds_write2_b32 v146, v95, v79 offset0:68 offset1:100
	ds_write2_b32 v146, v96, v80 offset0:136 offset1:168
	ds_write2_b32 v146, v97, v81 offset0:204 offset1:236
	v_subrev_u32_e32 v146, 0x1980, v146
	s_waitcnt lgkmcnt(0)
	ds_read_b128 v[66:69], v147
	ds_read_b128 v[70:73], v147 offset:16
	ds_read_b128 v[74:77], v147 offset:2176
	ds_read_b128 v[78:81], v147 offset:2192
	ds_read_b128 v[82:85], v147 offset:4352
	ds_read_b128 v[86:89], v147 offset:4368
	ds_read_b128 v[90:93], v147 offset:6528
	ds_read_b128 v[94:97], v147 offset:6544
	s_waitcnt lgkmcnt(6)
	v_cvt_pk_bf16_f32 v154, v66, v67
	v_cvt_pk_bf16_f32 v155, v68, v69
	v_cvt_pk_bf16_f32 v156, v70, v71
	v_cvt_pk_bf16_f32 v157, v72, v73
	global_store_dwordx4 v148, v[154:157], s[8:9]
	s_add_u32 s8, s8, 0xf000
	s_addc_u32 s9, s9, 0
	s_waitcnt lgkmcnt(4)
	v_cvt_pk_bf16_f32 v158, v74, v75
	v_cvt_pk_bf16_f32 v159, v76, v77
	v_cvt_pk_bf16_f32 v160, v78, v79
	v_cvt_pk_bf16_f32 v161, v80, v81
	global_store_dwordx4 v148, v[158:161], s[8:9]
	s_add_u32 s8, s8, 0xf000
	s_addc_u32 s9, s9, 0
	s_waitcnt lgkmcnt(2)
	v_cvt_pk_bf16_f32 v162, v82, v83
	v_cvt_pk_bf16_f32 v163, v84, v85
	v_cvt_pk_bf16_f32 v164, v86, v87
	v_cvt_pk_bf16_f32 v165, v88, v89
	global_store_dwordx4 v148, v[162:165], s[8:9]
	s_add_u32 s8, s8, 0xf000
	s_addc_u32 s9, s9, 0
	s_waitcnt lgkmcnt(0)
	v_cvt_pk_bf16_f32 v166, v90, v91
	v_cvt_pk_bf16_f32 v167, v92, v93
	v_cvt_pk_bf16_f32 v168, v94, v95
	v_cvt_pk_bf16_f32 v169, v96, v97
	global_store_dwordx4 v148, v[166:169], s[8:9]
	s_add_u32 s8, s8, 0xf000
	s_addc_u32 s9, s9, 0
	ds_write2_b32 v146, v50, v34 offset0:0 offset1:32
	ds_write2_b32 v146, v51, v35 offset0:68 offset1:100
	ds_write2_b32 v146, v52, v36 offset0:136 offset1:168
	ds_write2_b32 v146, v53, v37 offset0:204 offset1:236
	v_add_u32_e32 v146, 0x880, v146
	ds_write2_b32 v146, v54, v38 offset0:0 offset1:32
	ds_write2_b32 v146, v55, v39 offset0:68 offset1:100
	ds_write2_b32 v146, v56, v40 offset0:136 offset1:168
	ds_write2_b32 v146, v57, v41 offset0:204 offset1:236
	v_add_u32_e32 v146, 0x880, v146
	ds_write2_b32 v146, v58, v42 offset0:0 offset1:32
	ds_write2_b32 v146, v59, v43 offset0:68 offset1:100
	ds_write2_b32 v146, v60, v44 offset0:136 offset1:168
	ds_write2_b32 v146, v61, v45 offset0:204 offset1:236
	v_add_u32_e32 v146, 0x880, v146
	ds_write2_b32 v146, v62, v46 offset0:0 offset1:32
	ds_write2_b32 v146, v63, v47 offset0:68 offset1:100
	ds_write2_b32 v146, v64, v48 offset0:136 offset1:168
	ds_write2_b32 v146, v65, v49 offset0:204 offset1:236
	v_subrev_u32_e32 v146, 0x1980, v146
	s_waitcnt lgkmcnt(0)
	ds_read_b128 v[34:37], v147
	ds_read_b128 v[38:41], v147 offset:16
	ds_read_b128 v[42:45], v147 offset:2176
	ds_read_b128 v[46:49], v147 offset:2192
	ds_read_b128 v[50:53], v147 offset:4352
	ds_read_b128 v[54:57], v147 offset:4368
	ds_read_b128 v[58:61], v147 offset:6528
	ds_read_b128 v[62:65], v147 offset:6544
	s_waitcnt lgkmcnt(6)
	v_cvt_pk_bf16_f32 v154, v34, v35
	v_cvt_pk_bf16_f32 v155, v36, v37
	v_cvt_pk_bf16_f32 v156, v38, v39
	v_cvt_pk_bf16_f32 v157, v40, v41
	global_store_dwordx4 v148, v[154:157], s[8:9]
	s_add_u32 s8, s8, 0xf000
	s_addc_u32 s9, s9, 0
	s_waitcnt lgkmcnt(4)
	v_cvt_pk_bf16_f32 v158, v42, v43
	v_cvt_pk_bf16_f32 v159, v44, v45
	v_cvt_pk_bf16_f32 v160, v46, v47
	v_cvt_pk_bf16_f32 v161, v48, v49
	global_store_dwordx4 v148, v[158:161], s[8:9]
	s_add_u32 s8, s8, 0xf000
	s_addc_u32 s9, s9, 0
	s_waitcnt lgkmcnt(2)
	v_cvt_pk_bf16_f32 v162, v50, v51
	v_cvt_pk_bf16_f32 v163, v52, v53
	v_cvt_pk_bf16_f32 v164, v54, v55
	v_cvt_pk_bf16_f32 v165, v56, v57
	global_store_dwordx4 v148, v[162:165], s[8:9]
	s_add_u32 s8, s8, 0xf000
	s_addc_u32 s9, s9, 0
	s_waitcnt lgkmcnt(0)
	v_cvt_pk_bf16_f32 v166, v58, v59
	v_cvt_pk_bf16_f32 v167, v60, v61
	v_cvt_pk_bf16_f32 v168, v62, v63
	v_cvt_pk_bf16_f32 v169, v64, v65
	global_store_dwordx4 v148, v[166:169], s[8:9]
	s_add_u32 s8, s8, 0xf000
	s_addc_u32 s9, s9, 0
	ds_write2_b32 v146, v18, v2 offset0:0 offset1:32
	ds_write2_b32 v146, v19, v3 offset0:68 offset1:100
	ds_write2_b32 v146, v20, v4 offset0:136 offset1:168
	ds_write2_b32 v146, v21, v5 offset0:204 offset1:236
	v_add_u32_e32 v146, 0x880, v146
	ds_write2_b32 v146, v22, v6 offset0:0 offset1:32
	ds_write2_b32 v146, v23, v7 offset0:68 offset1:100
	ds_write2_b32 v146, v24, v8 offset0:136 offset1:168
	ds_write2_b32 v146, v25, v9 offset0:204 offset1:236
	v_add_u32_e32 v146, 0x880, v146
	ds_write2_b32 v146, v26, v10 offset0:0 offset1:32
	ds_write2_b32 v146, v27, v11 offset0:68 offset1:100
	ds_write2_b32 v146, v28, v12 offset0:136 offset1:168
	ds_write2_b32 v146, v29, v13 offset0:204 offset1:236
	v_add_u32_e32 v146, 0x880, v146
	ds_write2_b32 v146, v30, v14 offset0:0 offset1:32
	ds_write2_b32 v146, v31, v15 offset0:68 offset1:100
	ds_write2_b32 v146, v32, v16 offset0:136 offset1:168
	ds_write2_b32 v146, v33, v17 offset0:204 offset1:236
	v_subrev_u32_e32 v146, 0x1980, v146
	s_waitcnt lgkmcnt(0)
	ds_read_b128 v[2:5], v147
	ds_read_b128 v[6:9], v147 offset:16
	ds_read_b128 v[10:13], v147 offset:2176
	ds_read_b128 v[14:17], v147 offset:2192
	ds_read_b128 v[18:21], v147 offset:4352
	ds_read_b128 v[22:25], v147 offset:4368
	ds_read_b128 v[26:29], v147 offset:6528
	ds_read_b128 v[30:33], v147 offset:6544
	s_waitcnt lgkmcnt(6)
	v_cvt_pk_bf16_f32 v154, v2, v3
	v_cvt_pk_bf16_f32 v155, v4, v5
	v_cvt_pk_bf16_f32 v156, v6, v7
	v_cvt_pk_bf16_f32 v157, v8, v9
	global_store_dwordx4 v148, v[154:157], s[8:9]
	s_add_u32 s8, s8, 0xf000
	s_addc_u32 s9, s9, 0
	s_waitcnt lgkmcnt(4)
	v_cvt_pk_bf16_f32 v158, v10, v11
	v_cvt_pk_bf16_f32 v159, v12, v13
	v_cvt_pk_bf16_f32 v160, v14, v15
	v_cvt_pk_bf16_f32 v161, v16, v17
	global_store_dwordx4 v148, v[158:161], s[8:9]
	s_add_u32 s8, s8, 0xf000
	s_addc_u32 s9, s9, 0
	s_waitcnt lgkmcnt(2)
	v_cvt_pk_bf16_f32 v162, v18, v19
	v_cvt_pk_bf16_f32 v163, v20, v21
	v_cvt_pk_bf16_f32 v164, v22, v23
	v_cvt_pk_bf16_f32 v165, v24, v25
	global_store_dwordx4 v148, v[162:165], s[8:9]
	s_add_u32 s8, s8, 0xf000
	s_addc_u32 s9, s9, 0
	s_waitcnt lgkmcnt(0)
	v_cvt_pk_bf16_f32 v166, v26, v27
	v_cvt_pk_bf16_f32 v167, v28, v29
	v_cvt_pk_bf16_f32 v168, v30, v31
	v_cvt_pk_bf16_f32 v169, v32, v33
	global_store_dwordx4 v148, v[166:169], s[8:9]
	s_add_u32 s8, s8, 0xf000
	s_addc_u32 s9, s9, 0
	s_add_i32 s70, s70, s10
	s_cmp_lt_i32 s70, s71
	s_waitcnt lgkmcnt(0)
	s_barrier
	s_cbranch_scc0 .LBB0_209
	s_branch .LBB0_215

.Lmy_g0e_std:
	s_waitcnt vmcnt(0) lgkmcnt(0)
	s_barrier
	s_cmp_lt_u32 s5, 3
	ds_write2_b32 v230, v114, v98 offset1:32
	ds_write2_b32 v230, v115, v99 offset0:65 offset1:97
	ds_write2_b32 v230, v116, v100 offset0:130 offset1:162
	ds_write2_b32 v230, v117, v101 offset0:195 offset1:227
	ds_write2_b32 v239, v118, v102 offset0:8 offset1:40
	ds_write2_b32 v239, v119, v103 offset0:73 offset1:105
	ds_write2_b32 v239, v120, v104 offset0:138 offset1:170
	ds_write2_b32 v239, v121, v105 offset0:203 offset1:235
	ds_write2_b32 v240, v122, v106 offset0:16 offset1:48
	ds_write2_b32 v240, v123, v107 offset0:81 offset1:113
	ds_write2_b32 v240, v124, v108 offset0:146 offset1:178
	ds_write2_b32 v240, v125, v109 offset0:211 offset1:243
	ds_write2_b32 v241, v126, v110 offset0:24 offset1:56
	ds_write2_b32 v241, v127, v111 offset0:89 offset1:121
	ds_write2_b32 v241, v128, v112 offset0:154 offset1:186
	ds_write2_b32 v241, v129, v113 offset0:219 offset1:251
	s_cselect_b64 s[8:9], -1, 0
	s_cmp_gt_u32 s4, 26
	s_waitcnt lgkmcnt(0)
	s_cselect_b64 s[34:35], -1, 0
	ds_read2_b32 v[154:155], v231 offset0:16 offset1:17
	ds_read2_b32 v[128:129], v231 offset0:18 offset1:19
	ds_read2_b32 v[126:127], v231 offset0:20 offset1:21
	ds_read2_b32 v[124:125], v231 offset0:22 offset1:23
	ds_read2_b32 v[122:123], v231 offset1:1
	ds_read2_b32 v[120:121], v231 offset0:4 offset1:5
	ds_read2_b32 v[114:115], v231 offset0:6 offset1:7
	ds_read2_b32 v[116:117], v231 offset0:2 offset1:3
	ds_read2_b32 v[162:163], v231 offset0:8 offset1:9
	ds_read2_b32 v[160:161], v231 offset0:10 offset1:11
	ds_read2_b32 v[158:159], v231 offset0:12 offset1:13
	ds_read2_b32 v[156:157], v231 offset0:14 offset1:15
	ds_read2_b32 v[152:153], v231 offset0:24 offset1:25
	ds_read2_b32 v[150:151], v231 offset0:26 offset1:27
	ds_read2_b32 v[148:149], v231 offset0:28 offset1:29
	ds_read2_b32 v[146:147], v231 offset0:30 offset1:31
	s_or_b64 s[8:9], s[34:35], s[8:9]
	s_cmp_gt_u32 s4, 21
	s_cselect_b64 vcc, -1, 0
	s_cmp_lt_u32 s4, 11
	v_cndmask_b32_e32 v144, 1.0, v213, vcc
	s_cselect_b64 vcc, -1, 0
	s_and_b64 s[34:35], vcc, exec
	s_cselect_b32 s7, s84, s86
	v_readlane_b32 s34, v242, 4
	s_cselect_b32 s5, s85, s87
	v_readlane_b32 s35, v242, 5
	s_add_u32 s34, s7, s34
	s_addc_u32 s35, s5, s35
	s_cmp_lt_i32 s4, 2
	v_mov_b32_e32 v141, v1
	s_cselect_b64 s[4:5], -1, 0
	v_lshl_add_u64 v[142:143], s[34:35], 0, v[140:141]
	s_and_b64 s[34:35], s[4:5], exec
	s_cselect_b32 s34, s28, s94
	v_readlane_b32 s36, v242, 12
	s_cselect_b32 s7, s29, s95
	v_readlane_b32 s37, v242, 13
	s_add_u32 s34, s34, s36
	s_addc_u32 s35, s7, s37
	s_movk_i32 s7, 0xf80
	v_and_or_b32 v0, v238, s7, v131
	s_waitcnt lgkmcnt(0)
	v_mul_u32_u24_e32 v0, 0x48, v0
	v_lshlrev_b32_e32 v0, 2, v0
	v_cndmask_b32_e32 v139, 1.0, v214, vcc
	v_lshl_add_u64 v[118:119], s[92:93], 0, v[0:1]
	s_mov_b64 s[96:97], -1
	s_and_b64 vcc, exec, s[30:31]
	s_cbranch_vccz .LBB0_239
	s_and_b64 vcc, exec, s[98:99]
	s_cbranch_vccz .LBB0_234
	s_and_b64 vcc, exec, s[2:3]
	s_cbranch_vccz .LBB0_227
	s_or_b64 s[68:69], s[82:83], s[8:9]
	s_andn2_b64 vcc, exec, s[68:69]
	s_waitcnt lgkmcnt(3)
	v_mov_b64_e32 v[110:111], v[152:153]
	s_waitcnt lgkmcnt(2)
	v_mov_b64_e32 v[112:113], v[150:151]
	s_waitcnt lgkmcnt(1)
	v_mov_b64_e32 v[172:173], v[148:149]
	s_waitcnt lgkmcnt(0)
	v_mov_b64_e32 v[174:175], v[146:147]
	v_mov_b64_e32 v[176:177], v[154:155]
	v_mov_b64_e32 v[178:179], v[128:129]
	v_mov_b64_e32 v[180:181], v[126:127]
	v_mov_b64_e32 v[190:191], v[124:125]
	v_mov_b64_e32 v[164:165], v[162:163]
	v_mov_b64_e32 v[166:167], v[160:161]
	v_mov_b64_e32 v[168:169], v[158:159]
	v_mov_b64_e32 v[170:171], v[156:157]
	v_mov_b64_e32 v[182:183], v[122:123]
	v_mov_b64_e32 v[188:189], v[116:117]
	v_mov_b64_e32 v[186:187], v[120:121]
	v_mov_b64_e32 v[184:185], v[114:115]
	s_cbranch_vccnz .LBB0_226
	v_mul_f32_e32 v0, 0xbfb8aa3b, v122
	v_exp_f32_e32 v0, v0
	v_mul_f32_e32 v98, 0xbfb8aa3b, v123
	v_exp_f32_e32 v98, v98
	v_mul_f32_e32 v100, 0xbfb8aa3b, v117
	v_add_f32_e32 v0, 1.0, v0
	v_exp_f32_e32 v100, v100
	v_add_f32_e32 v99, 1.0, v98
	v_rcp_f32_e32 v98, v0
	v_mul_f32_e32 v0, 0xbfb8aa3b, v116
	v_exp_f32_e32 v0, v0
	v_rcp_f32_e32 v99, v99
	v_add_f32_e32 v0, 1.0, v0
	v_pk_mul_f32 v[182:183], v[122:123], v[98:99]
	v_rcp_f32_e32 v98, v0
	v_add_f32_e32 v0, 1.0, v100
	v_rcp_f32_e32 v99, v0
	v_mul_f32_e32 v0, 0xbfb8aa3b, v120
	v_exp_f32_e32 v0, v0
	v_mul_f32_e32 v100, 0xbfb8aa3b, v121
	v_exp_f32_e32 v100, v100
	v_pk_mul_f32 v[188:189], v[116:117], v[98:99]
	v_add_f32_e32 v0, 1.0, v0
	v_rcp_f32_e32 v98, v0
	v_add_f32_e32 v0, 1.0, v100
	v_rcp_f32_e32 v99, v0
	v_mul_f32_e32 v0, 0xbfb8aa3b, v114
	v_exp_f32_e32 v0, v0
	v_mul_f32_e32 v100, 0xbfb8aa3b, v115
	v_exp_f32_e32 v100, v100
	v_pk_mul_f32 v[186:187], v[120:121], v[98:99]
	v_add_f32_e32 v0, 1.0, v0
	v_rcp_f32_e32 v98, v0
	v_add_f32_e32 v0, 1.0, v100
	v_rcp_f32_e32 v99, v0
	v_mul_f32_e32 v0, 0xbfb8aa3b, v162
	v_exp_f32_e32 v0, v0
	v_mul_f32_e32 v100, 0xbfb8aa3b, v163
	v_exp_f32_e32 v100, v100
	v_pk_mul_f32 v[184:185], v[114:115], v[98:99]
	v_add_f32_e32 v0, 1.0, v0
	v_rcp_f32_e32 v98, v0
	v_add_f32_e32 v0, 1.0, v100
	v_rcp_f32_e32 v99, v0
	v_mul_f32_e32 v0, 0xbfb8aa3b, v160
	v_exp_f32_e32 v0, v0
	v_mul_f32_e32 v100, 0xbfb8aa3b, v161
	v_exp_f32_e32 v100, v100
	v_pk_mul_f32 v[164:165], v[162:163], v[98:99]
	v_add_f32_e32 v0, 1.0, v0
	v_rcp_f32_e32 v98, v0
	v_add_f32_e32 v0, 1.0, v100
	v_rcp_f32_e32 v99, v0
	v_mul_f32_e32 v0, 0xbfb8aa3b, v158
	v_exp_f32_e32 v0, v0
	v_mul_f32_e32 v100, 0xbfb8aa3b, v159
	v_exp_f32_e32 v100, v100
	v_pk_mul_f32 v[166:167], v[160:161], v[98:99]
	v_add_f32_e32 v0, 1.0, v0
	v_rcp_f32_e32 v98, v0
	v_add_f32_e32 v0, 1.0, v100
	v_rcp_f32_e32 v99, v0
	v_mul_f32_e32 v0, 0xbfb8aa3b, v156
	v_exp_f32_e32 v0, v0
	v_mul_f32_e32 v100, 0xbfb8aa3b, v157
	v_exp_f32_e32 v100, v100
	v_pk_mul_f32 v[168:169], v[158:159], v[98:99]
	v_add_f32_e32 v0, 1.0, v0
	v_rcp_f32_e32 v98, v0
	v_add_f32_e32 v0, 1.0, v100
	v_rcp_f32_e32 v99, v0
	v_mul_f32_e32 v0, 0xbfb8aa3b, v154
	v_exp_f32_e32 v0, v0
	v_mul_f32_e32 v100, 0xbfb8aa3b, v155
	v_exp_f32_e32 v100, v100
	v_pk_mul_f32 v[170:171], v[156:157], v[98:99]
	v_add_f32_e32 v0, 1.0, v0
	v_rcp_f32_e32 v98, v0
	v_add_f32_e32 v0, 1.0, v100
	v_rcp_f32_e32 v99, v0
	v_mul_f32_e32 v0, 0xbfb8aa3b, v128
	v_exp_f32_e32 v0, v0
	v_mul_f32_e32 v100, 0xbfb8aa3b, v129
	v_exp_f32_e32 v100, v100
	v_pk_mul_f32 v[176:177], v[154:155], v[98:99]
	v_add_f32_e32 v0, 1.0, v0
	v_rcp_f32_e32 v98, v0
	v_add_f32_e32 v0, 1.0, v100
	v_rcp_f32_e32 v99, v0
	v_mul_f32_e32 v0, 0xbfb8aa3b, v126
	v_exp_f32_e32 v0, v0
	v_mul_f32_e32 v100, 0xbfb8aa3b, v127
	v_exp_f32_e32 v100, v100
	v_pk_mul_f32 v[178:179], v[128:129], v[98:99]
	v_add_f32_e32 v0, 1.0, v0
	v_rcp_f32_e32 v98, v0
	v_add_f32_e32 v0, 1.0, v100
	v_rcp_f32_e32 v99, v0
	v_mul_f32_e32 v0, 0xbfb8aa3b, v124
	v_exp_f32_e32 v0, v0
	v_mul_f32_e32 v100, 0xbfb8aa3b, v125
	v_exp_f32_e32 v100, v100
	v_pk_mul_f32 v[180:181], v[126:127], v[98:99]
	v_add_f32_e32 v0, 1.0, v0
	v_rcp_f32_e32 v98, v0
	v_add_f32_e32 v0, 1.0, v100
	v_rcp_f32_e32 v99, v0
	v_mul_f32_e32 v0, 0xbfb8aa3b, v152
	v_exp_f32_e32 v0, v0
	v_mul_f32_e32 v100, 0xbfb8aa3b, v153
	v_exp_f32_e32 v100, v100
	v_pk_mul_f32 v[190:191], v[124:125], v[98:99]
	v_add_f32_e32 v0, 1.0, v0
	v_mul_f32_e32 v99, 0xbfb8aa3b, v150
	v_rcp_f32_e32 v98, v0
	v_add_f32_e32 v0, 1.0, v100
	v_exp_f32_e32 v100, v99
	v_mul_f32_e32 v99, 0xbfb8aa3b, v151
	v_exp_f32_e32 v101, v99
	v_rcp_f32_e32 v99, v0
	v_add_f32_e32 v0, 1.0, v100
	v_rcp_f32_e32 v100, v0
	v_add_f32_e32 v0, 1.0, v101
	v_mul_f32_e32 v101, 0xbfb8aa3b, v148
	v_exp_f32_e32 v102, v101
	v_mul_f32_e32 v101, 0xbfb8aa3b, v149
	v_exp_f32_e32 v103, v101
	v_rcp_f32_e32 v101, v0
	v_add_f32_e32 v0, 1.0, v102
	v_rcp_f32_e32 v102, v0
	v_add_f32_e32 v0, 1.0, v103
	v_mul_f32_e32 v103, 0xbfb8aa3b, v146
	v_exp_f32_e32 v104, v103
	v_mul_f32_e32 v103, 0xbfb8aa3b, v147
	v_exp_f32_e32 v105, v103
	v_rcp_f32_e32 v103, v0
	v_add_f32_e32 v0, 1.0, v104
	v_rcp_f32_e32 v104, v0
	v_add_f32_e32 v0, 1.0, v105
	v_rcp_f32_e32 v105, v0
	v_pk_mul_f32 v[110:111], v[152:153], v[98:99]
	v_pk_mul_f32 v[112:113], v[150:151], v[100:101]
	v_pk_mul_f32 v[172:173], v[148:149], v[102:103]
	v_pk_mul_f32 v[174:175], v[146:147], v[104:105]
